# adds phase-0 first-round item rotation (filter items moved to the CUs with 11 items) on top of mod_item rewrite + bare v_sqrt in LRU gate math
# baseline (speedup 1.0000x reference)
; DEVI void phase0(const Params& p) {
;     ...
;   for (int it = blockIdx.x; it < NIT; it += gridDim.x) {
;     asm volatile("" ::: "memory");
;     int r = it;
;     if (r < N_FIL) {
;       if (r < 64) filter_item(p, 0, 4096, (u16*)(p.ws + OFF_KF), r);
;       else if (r < 128) filter_item(p, 1, 4096, (u16*)(p.ws + OFF_KF) + (size_t)256 * 8192, r - 64);
;       else filter_item(p, 0, 256, (u16*)(p.ws + OFF_KFC), r - 128);
;       continue;
;     }
;     r -= N_FIL;
;     if (r < N_MOD_IT) { mod_item(p, r); continue; } r -= N_MOD_IT;
;     if (r < 4 * I_W1) { const int mi = r / I_W1; transpose_item(p, p.in[7] + (size_t)mi * 1024 * 5632, 1024, 5632, (u16*)(p.ws + OFF_W1T) + (size_t)mi * 5632 * 1024, 1, r % I_W1); continue; } r -= 4 * I_W1;
;     if (r < 4 * I_W2) { const int mi = r / I_W2; transpose_item(p, p.in[8] + (size_t)mi * 2816 * 1024, 2816, 1024, (u16*)(p.ws + OFF_W2T) + (size_t)mi * 1024 * 2816, 0, r % I_W2); continue; } r -= 4 * I_W2;
;     if (r < 2 * I_WIN) { const int mi = r / I_WIN; transpose_item(p, p.in[9] + (size_t)mi * 1024 * 2048, 1024, 2048, (u16*)(p.ws + OFF_WINT) + (size_t)mi * 2048 * 1024, 2, r % I_WIN); continue; } r -= 2 * I_WIN;
;     { const int mi = r / I_WO; transpose_item(p, p.in[10] + (size_t)mi * 1024 * 1024, 1024, 1024, (u16*)(p.ws + OFF_WOT) + (size_t)mi * 1024 * 1024, 0, r % I_WO); }
;   }
.LBB0_6:
	s_load_dwordx16 s[36:51], s[0:1], 0x0
	s_load_dwordx16 s[16:31], s[0:1], 0x40
	s_andn2_b64 vcc, exec, s[4:5]
	s_waitcnt lgkmcnt(0)
	v_writelane_b32 v252, s36, 14
	s_nop 1
	v_writelane_b32 v252, s37, 15
	v_writelane_b32 v252, s38, 16
	v_writelane_b32 v252, s39, 17
	v_writelane_b32 v252, s40, 18
	v_writelane_b32 v252, s41, 19
	v_writelane_b32 v252, s42, 20
	v_writelane_b32 v252, s43, 21
	v_writelane_b32 v252, s44, 22
	v_writelane_b32 v252, s45, 23
	v_writelane_b32 v252, s46, 24
	v_writelane_b32 v252, s47, 25
	v_writelane_b32 v252, s48, 26
	v_writelane_b32 v252, s49, 27
	v_writelane_b32 v252, s50, 28
	v_writelane_b32 v252, s51, 29
	v_writelane_b32 v252, s16, 30
	s_nop 1
	v_writelane_b32 v252, s17, 31
	v_writelane_b32 v252, s18, 32
	v_writelane_b32 v252, s19, 33
	v_writelane_b32 v252, s20, 34
	v_writelane_b32 v252, s21, 35
	v_writelane_b32 v252, s22, 36
	v_writelane_b32 v252, s23, 37
	v_writelane_b32 v252, s24, 38
	v_writelane_b32 v252, s25, 39
	v_writelane_b32 v252, s26, 40
	v_writelane_b32 v252, s27, 41
	v_writelane_b32 v252, s28, 42
	v_writelane_b32 v252, s29, 43
	v_writelane_b32 v252, s30, 44
	v_writelane_b32 v252, s31, 45
	s_load_dwordx16 s[16:31], s[0:1], 0x80
	s_waitcnt lgkmcnt(0)
	v_writelane_b32 v252, s16, 46
	s_nop 1
	v_writelane_b32 v252, s17, 47
	v_writelane_b32 v252, s18, 48
	v_writelane_b32 v252, s19, 49
	v_writelane_b32 v252, s20, 50
	v_writelane_b32 v252, s21, 51
	v_writelane_b32 v252, s22, 52
	v_writelane_b32 v252, s23, 53
	v_writelane_b32 v252, s24, 54
	v_writelane_b32 v252, s25, 55
	v_writelane_b32 v252, s26, 56
	v_writelane_b32 v252, s27, 57
	v_writelane_b32 v252, s28, 58
	v_writelane_b32 v252, s29, 59
	v_writelane_b32 v252, s30, 60
	v_writelane_b32 v252, s31, 61
	s_cbranch_vccnz .LBB0_572
	s_add_u32 s2, s70, 0x1d100000
	v_readlane_b32 s0, v252, 13
	s_addc_u32 s68, s71, 0
	s_and_b32 s33, s0, 0xffffffc0
	s_add_u32 s69, s70, 0x1c900000
	s_addc_u32 s72, s71, 0
	s_add_u32 s73, s70, 0x1b300000
	s_addc_u32 s74, s71, 0
	s_add_u32 s75, s70, 0x18700000
	s_addc_u32 s54, s71, 0
	s_add_u32 s55, s70, 0x1d500000
	s_addc_u32 s56, s71, 0
	s_add_u32 s14, s70, 0x1dda2000
	s_addc_u32 s15, s71, 0
	s_add_u32 s16, s70, 0x1d9a2000
	v_readlane_b32 s36, v252, 46
	s_addc_u32 s17, s71, 0
	v_readlane_b32 s44, v252, 54
	v_readlane_b32 s45, v252, 55
	s_add_u32 s18, s44, 0x2100
	v_readlane_b32 s46, v252, 56
	s_addc_u32 s19, s45, 0
	v_readlane_b32 s47, v252, 57
	s_add_u32 s20, s46, 0x100
	v_readlane_b32 s48, v252, 58
	s_addc_u32 s21, s47, 0
	v_readlane_b32 s49, v252, 59
	s_add_u32 s22, s48, 0x8000
	v_readlane_b32 s50, v252, 60
	s_addc_u32 s23, s49, 0
	v_readlane_b32 s51, v252, 61
	s_add_u32 s24, s50, 0x200
	s_addc_u32 s25, s51, 0
	v_readlane_b32 s4, v252, 5
	v_readlane_b32 s5, v252, 6
	s_add_u32 s26, s4, 0x100
	v_readlane_b32 s6, v252, 7
	s_addc_u32 s27, s5, 0
	v_readlane_b32 s7, v252, 8
	s_add_u32 s28, s6, 0x20000
	s_addc_u32 s29, s7, 0
	s_add_u32 s34, s70, 0x1d5a2000
	s_addc_u32 s35, s71, 0
	v_mov_b32_e32 v119, 0
	s_movk_i32 s57, 0x404
	s_movk_i32 s58, 0x1600
	s_movk_i32 s59, 0x5800
	s_movk_i32 s60, 0x90
	s_mov_b32 s61, 0x9000
	v_mov_b32_e32 v123, 0x38d1b717
	v_mov_b32_e32 v148, 0xc0447cbd
	v_mov_b32_e32 v149, 0x100
	v_mov_b32_e32 v150, 0x1000
	s_add_i32 s62, 0, 0xa400
	s_add_i32 s63, 0, 0x6400
	v_readlane_b32 s64, v252, 0
	s_mov_b32 s53, 0
	v_readlane_b32 s37, v252, 47
	v_readlane_b32 s38, v252, 48
	v_readlane_b32 s39, v252, 49
	v_readlane_b32 s40, v252, 50
	v_readlane_b32 s41, v252, 51
	v_readlane_b32 s42, v252, 52
	v_readlane_b32 s43, v252, 53
	v_readlane_b32 s8, v252, 9
	v_readlane_b32 s9, v252, 10
	v_readlane_b32 s10, v252, 11
	v_readlane_b32 s11, v252, 12
	s_cmpk_eq_u32 s3, 0x100
	s_cbranch_scc0 .Lmy_rot_skip
	s_add_i32 s64, s64, 0x84
	s_and_b32 s64, s64, 0xff
.Lmy_rot_skip:
	s_branch .LBB0_10
.LBB0_8:
	s_or_b64 exec, exec, s[0:1]
	s_barrier
.LBB0_9:
	s_cmpk_eq_u32 s3, 0x100
	s_cbranch_scc0 .Lmy_rot_noadj
	s_cmpk_lt_u32 s64, 0x100
	s_cbranch_scc0 .Lmy_rot_noadj
	v_readlane_b32 s64, v252, 0
	s_nop 3
